# RG-LRU lane-channel map made contiguous (8 ch per lane): paired 8B gathers merged to 16B, x taken from the K-fragment registers instead of re-gathered, 16B output stores
# speedup vs baseline: 1.0124x; 1.0050x over previous
; #define LAS __attribute__((address_space(3)))
; __device__ __forceinline__ void lru_fused(const bf16* XC, const bf16* Wrg_t, const bf16* PROJ, bf16* YL, const float* b_a, const float* b_x, const float* sp8,
;                                           LAS unsigned char* lds, int tid, int lane, int wave, int vcu, int G) {
;     ...
;     for (int vq = vcu; vq < 256; vq += G) {
;         const int h = vq >> 4, s = (vq >> 1) & 7, bsel = vq & 1;
;         __syncthreads();
;         { const int n = tid >> 3, p = tid & 7, chl = s * 32 + (n & 31), srow = h * 512 + (chl >> 7) * 256 + (n >> 5) * 128 + (chl & 127);
;           const v4u* src = (const v4u*)(Wrg_t + (size_t)srow * HD + p * 32); LAS v4u* dst = (LAS v4u*)(lds + n * RG_PITCH + p * 64);
; #pragma unroll
;           for (int q = 0; q < 4; ++q) dst[q] = src[q]; }
;         __syncthreads();
;         const int c0 = h * HD + s * 32;
;         f32x4 ba[2], bx[2], sp[2];
; #pragma unroll
;         for (int c2 = 0; c2 < 2; ++c2) { const int ch = c0 + 16 * c2 + 4 * fq; ba[c2] = *(const f32x4*)(b_a + ch); bx[c2] = *(const f32x4*)(b_x + ch); sp[c2] = *(const f32x4*)(sp8 + ch) * 1.44269504088896f; }
;         const bf16* abase = XC + h * HD + 8 * fq; const bf16* xbase = XC + c0 + 4 * fq; const bf16* gbase = PROJ + D + c0 + 4 * fq; bf16* obase = YL + c0 + 4 * fq;
;         const LAS unsigned char* bl = lds + fr * RG_PITCH + 16 * fq;
;         LAS float* xch = (LAS float*)(lds + LRU_XOFF);
.LBB0_450:
	s_add_u32 s0, s12, 0x46e00000
	s_addc_u32 s1, s13, 0
	s_add_u32 s4, s12, 0x46e10000
	s_addc_u32 s5, s13, 0
	s_cmp_lt_i32 s28, 5
	s_cselect_b64 s[2:3], -1, 0
	s_cmp_gt_i32 s29, 4
	s_cselect_b64 s[6:7], -1, 0
	s_and_b64 s[2:3], s[2:3], s[6:7]
	s_mov_b64 s[78:79], s[12:13]
	s_andn2_b64 vcc, exec, s[2:3]
	s_cbranch_vccnz .LBB0_537
	s_cmpk_gt_i32 s34, 0xff
	s_cbranch_scc1 .LBB0_478
	s_waitcnt vmcnt(0)
	v_and_b32_e32 v2, 7, v0
	v_lshlrev_b32_e32 v4, 6, v2
	v_mov_b32_e32 v2, 0
	v_readlane_b32 s2, v249, 25
	v_mov_b32_e32 v5, v2
	v_readlane_b32 s3, v249, 26
	v_lshrrev_b32_e32 v3, 4, v178
	v_lshrrev_b32_e32 v6, 3, v0
	v_lshl_add_u64 v[112:113], s[2:3], 0, v[4:5]
	s_movk_i32 s6, 0x220
	v_readlane_b32 s2, v249, 35
	v_mad_u32_u24 v5, v6, s6, 0
	v_lshlrev_b32_e32 v6, 4, v3
	v_mov_b32_e32 v7, v2
	v_and_b32_e32 v8, 48, v178
	v_mov_b32_e32 v9, v2
	v_readlane_b32 s3, v249, 36
	s_mov_b64 s[16:17], s[78:79]
	v_and_b32_e32 v110, 15, v0
	v_lshl_add_u64 v[114:115], s[2:3], 0, v[8:9]
	v_lshl_add_u64 v[116:117], s[2:3], 0, v[6:7]
	v_lshl_add_u64 v[6:7], s[16:17], 0, v[6:7]
	s_mov_b64 s[2:3], 0x18e02000
	v_lshl_add_u64 v[118:119], v[6:7], 0, s[2:3]
	v_readlane_b32 s2, v249, 38
	v_lshlrev_b32_e32 v165, 2, v3
	v_and_b32_e32 v3, 12, v110
	v_lshlrev_b32_e32 v3, 1, v3
	v_and_or_b32 v3, v110, 3, v3
	v_mad_u32_u24 v3, v3, s6, 0
	s_mov_b32 s8, s2
	s_lshl_b32 s6, s2, 5
	s_cmp_eq_u32 s8, 7
	s_cselect_b64 s[12:13], -1, 0
	v_cmp_eq_u32_e32 vcc, 0, v110
	s_and_b64 s[40:41], vcc, s[12:13]
	v_readlane_b32 s7, v249, 37
	s_cmp_gt_u32 s7, 63
	s_cselect_b64 s[42:43], -1, 0
	s_cmpk_gt_u32 s7, 0x7f
	s_cselect_b64 s[44:45], -1, 0
	s_cmpk_gt_u32 s7, 0xbf
	v_and_b32_e32 v9, 48, v0
	s_cselect_b64 s[48:49], -1, 0
	s_cmpk_gt_u32 s7, 0xff
	s_cselect_b64 s[50:51], -1, 0
	s_cmpk_gt_u32 s7, 0x13f
	v_add_u32_e32 v170, v3, v9
	v_mbcnt_lo_u32_b32 v3, -1, 0
	v_lshrrev_b32_e32 v10, 1, v0
	s_cselect_b64 s[52:53], -1, 0
	s_cmpk_gt_u32 s7, 0x17f
	v_mbcnt_hi_u32_b32 v3, -1, v3
	v_readlane_b32 s3, v249, 39
	v_or_b32_e32 v166, s6, v110
	v_readlane_b32 s36, v249, 31
	s_cselect_b64 s[54:55], -1, 0
	s_cmpk_gt_u32 s7, 0x1bf
	v_and_b32_e32 v6, 48, v0
	v_mov_b32_e32 v7, v2
	v_and_or_b32 v3, v3, 64, v178
	v_bfe_u32 v1, v0, 3, 5
	v_and_b32_e32 v164, 0x80, v10
	s_mov_b32 s39, 0
	v_mov_b32_e32 v111, v2
	v_add_u32_e32 v167, 0, v8
	v_cmp_eq_u32_e64 s[2:3], 15, v110
	v_readlane_b32 s37, v249, 32
	s_cselect_b64 s[58:59], -1, 0
	v_lshl_add_u64 v[120:121], s[16:17], 0, v[6:7]
	v_or_b32_e32 v168, 16, v166
	s_lshl_b32 s7, s34, 13
	s_lshl_b32 s8, s10, 13
	s_lshl_b32 s11, s34, 4
	s_lshl_b32 s12, s10, 4
	v_add_u32_e32 v169, v5, v4
	s_mov_b32 s62, 0x3fb8aa3b
	s_mov_b32 s13, 0xa000
	s_mov_b32 s16, 0xa0000
	v_mov_b32_e32 v171, 0xc0135761
	s_mov_b32 s17, 0x50e00000
	v_lshl_or_b32 v172, v3, 2, 60
	s_mov_b32 s18, s34
	s_branch .LBB0_454

; #define LAS __attribute__((address_space(3)))
; __device__ __forceinline__ void lru_fused(const bf16* XC, const bf16* Wrg_t, const bf16* PROJ, bf16* YL, const float* b_a, const float* b_x, const float* sp8,
;                                           LAS unsigned char* lds, int tid, int lane, int wave, int vcu, int G) {
;     ...
;         { const int n = tid >> 3, p = tid & 7, chl = s * 32 + (n & 31), srow = h * 512 + (chl >> 7) * 256 + (n >> 5) * 128 + (chl & 127);
;           const v4u* src = (const v4u*)(Wrg_t + (size_t)srow * HD + p * 32); LAS v4u* dst = (LAS v4u*)(lds + n * RG_PITCH + p * 64);
; #pragma unroll
;           for (int q = 0; q < 4; ++q) dst[q] = src[q]; }
;         __syncthreads();
;         const int c0 = h * HD + s * 32;
;         f32x4 ba[2], bx[2], sp[2];
; #pragma unroll
;         for (int c2 = 0; c2 < 2; ++c2) { const int ch = c0 + 16 * c2 + 4 * fq; ba[c2] = *(const f32x4*)(b_a + ch); bx[c2] = *(const f32x4*)(b_x + ch); sp[c2] = *(const f32x4*)(sp8 + ch) * 1.44269504088896f; }
;         const bf16* abase = XC + h * HD + 8 * fq; const bf16* xbase = XC + c0 + 4 * fq; const bf16* gbase = PROJ + D + c0 + 4 * fq; bf16* obase = YL + c0 + 4 * fq;
;         const LAS unsigned char* bl = lds + fr * RG_PITCH + 16 * fq;
;         LAS float* xch = (LAS float*)(lds + LRU_XOFF);
;         bf16x8 af[2][8]; v2u xq[2][2], gq[2][2];
;         { const size_t row0 = (size_t)bsel * SEQ + (size_t)wave * 32;
; #pragma unroll
;           for (int r2 = 0; r2 < 2; ++r2) { const size_t ro = (row0 + 16 * r2 + fr) * D, rg = (row0 + 16 * r2 + fr) * NIN;
; #pragma unroll
;               for (int kb = 0; kb < 8; ++kb) af[r2][kb] = *(const bf16x8*)(abase + ro + 32 * kb);
; #pragma unroll
;               for (int c2 = 0; c2 < 2; ++c2) { xq[r2][c2] = *(const v2u*)(xbase + ro + 16 * c2); gq[r2][c2] = *(const v2u*)(gbase + rg + 16 * c2); } } }
.LBB0_454:
	s_and_b32 s22, s7, 0x2000
	s_and_b32 s23, s11, 0xe0
	s_add_i32 s38, s6, s22
	s_add_u32 s19, s38, 0x100
	s_addc_u32 s20, 0, 0
	s_lshl_b32 s26, s18, 4
	s_ashr_i32 s21, s18, 4
	s_lshl_b32 s24, s18, 5
	s_and_b32 s25, s26, 0x60
	s_and_b32 s24, s24, 0x100
	v_lshl_or_b32 v3, s21, 9, v164
	v_or_b32_e32 v4, s25, v1
	v_or3_b32 v4, v3, v4, s24
	v_ashrrev_i32_e32 v5, 31, v4
	v_lshlrev_b64 v[4:5], 9, v[4:5]
	v_lshl_add_u64 v[16:17], v[112:113], 0, v[4:5]
	s_waitcnt lgkmcnt(0)
	s_barrier
	global_load_dwordx4 v[4:7], v[16:17], off
	global_load_dwordx4 v[8:11], v[16:17], off offset:16
	global_load_dwordx4 v[12:15], v[16:17], off offset:32
	s_nop 0
	global_load_dwordx4 v[16:19], v[16:17], off offset:48
	s_and_b32 s28, s26, 0xe0
	s_lshl_b32 s26, s21, 8
	s_or_b32 s28, s26, s28
	s_lshl_b32 s27, s18, 13
	s_ashr_i32 s29, s28, 31
	s_and_b32 s21, s27, 0x2000
	v_lshl_or_b32 v22, v165, 1, s28
	s_lshl_b64 s[28:29], s[28:29], 1
	v_mov_b32_e32 v21, v2
	s_ashr_i32 s27, s26, 31
	v_add_u32_e32 v20, s21, v166
	v_ashrrev_i32_e32 v23, 31, v22
	v_or_b32_e32 v26, 4, v22
	v_lshl_add_u64 v[126:127], v[118:119], 0, s[28:29]
	v_lshl_add_u64 v[122:123], s[26:27], 1, v[114:115]
	v_lshlrev_b64 v[24:25], 13, v[20:21]
	v_lshlrev_b64 v[22:23], 2, v[22:23]
	v_ashrrev_i32_e32 v27, 31, v26
	v_lshl_add_u64 v[124:125], v[116:117], 0, s[28:29]
	v_mad_u64_u32 v[42:43], s[28:29], v20, s13, v[126:127]
	s_mov_b64 s[24:25], 0xa0000
	v_lshl_add_u64 v[38:39], v[122:123], 0, v[24:25]
	v_lshl_add_u64 v[28:29], s[56:57], 0, v[22:23]
	v_lshl_add_u64 v[30:31], s[60:61], 0, v[22:23]
	v_lshl_add_u64 v[22:23], s[36:37], 0, v[22:23]
	v_lshl_add_u64 v[26:27], v[26:27], 2, s[36:37]
	v_lshl_add_u64 v[40:41], v[124:125], 0, v[24:25]
	v_or_b32_e32 v24, 0x20000, v24
	v_add_co_u32_e32 v100, vcc, s16, v42
	v_lshl_add_u64 v[94:95], v[122:123], 0, v[24:25]
	v_lshl_add_u64 v[96:97], v[124:125], 0, v[24:25]
	v_lshl_add_u64 v[98:99], v[42:43], 0, s[24:25]
	v_addc_co_u32_e32 v101, vcc, 0, v43, vcc
	s_mov_b64 s[64:65], 0
	s_mov_b32 s21, 32
	s_waitcnt vmcnt(3)
	ds_write_b128 v169, v[4:7]
	s_waitcnt vmcnt(2)
	ds_write_b128 v169, v[8:11] offset:16
	s_waitcnt vmcnt(1)
	ds_write_b128 v169, v[12:15] offset:32
	s_waitcnt vmcnt(0)
	ds_write_b128 v169, v[16:19] offset:48
	s_waitcnt lgkmcnt(0)
	s_barrier
	global_load_dwordx4 v[6:9], v[28:29], off
	global_load_dwordx4 v[10:13], v[28:29], off offset:16
	global_load_dwordx4 v[14:17], v[30:31], off
	global_load_dwordx4 v[18:21], v[30:31], off offset:16
	global_load_dwordx4 v[86:89], v[22:23], off
	global_load_dwordx4 v[90:93], v[26:27], off
	global_load_dwordx4 v[70:73], v[38:39], off
	global_load_dwordx4 v[62:65], v[38:39], off offset:64
	global_load_dwordx4 v[54:57], v[38:39], off offset:128
	global_load_dwordx4 v[46:49], v[38:39], off offset:192
	global_load_dwordx4 v[34:37], v[38:39], off offset:256
	global_load_dwordx4 v[30:33], v[38:39], off offset:320
	global_load_dwordx4 v[26:29], v[38:39], off offset:384
	global_load_dwordx4 v[22:25], v[38:39], off offset:448
	global_load_dwordx2 v[142:143], v[40:41], off
	global_load_dwordx2 v[158:159], v[42:43], off
	global_load_dwordx2 v[152:153], v[42:43], off offset:8
	global_load_dwordx2 v[144:145], v[40:41], off offset:8
	global_load_dwordx4 v[82:85], v[94:95], off
	global_load_dwordx4 v[78:81], v[94:95], off offset:64
	global_load_dwordx4 v[74:77], v[94:95], off offset:128
	global_load_dwordx4 v[66:69], v[94:95], off offset:192
	global_load_dwordx4 v[58:61], v[94:95], off offset:256
	global_load_dwordx4 v[50:53], v[94:95], off offset:320
	global_load_dwordx4 v[42:45], v[94:95], off offset:384
	global_load_dwordx4 v[38:41], v[94:95], off offset:448
	global_load_dwordx2 v[148:149], v[96:97], off
	global_load_dwordx2 v[146:147], v[100:101], off
	global_load_dwordx2 v[150:151], v[96:97], off offset:8
	global_load_dwordx2 v[140:141], v[98:99], off offset:8
	v_add_u32_e32 v4, s22, v168
	s_or_b32 s22, s26, s23
	v_mov_b32_e32 v5, v2
	v_lshl_add_u64 v[94:95], v[110:111], 0, s[38:39]
	s_ashr_i32 s23, s22, 31
	v_lshlrev_b64 v[4:5], 13, v[4:5]
	v_lshlrev_b64 v[94:95], 13, v[94:95]
	s_lshl_b64 s[22:23], s[22:23], 1
	v_lshl_add_u64 v[4:5], v[4:5], 0, s[22:23]
	v_lshl_add_u64 v[94:95], v[94:95], 0, s[22:23]
	v_lshl_add_u64 v[128:129], v[120:121], 0, v[4:5]
	v_lshl_add_u64 v[130:131], v[120:121], 0, v[94:95]
	s_mov_b32 s22, 0
	s_waitcnt vmcnt(25)
	v_pk_mul_f32 v[132:133], v[88:89], s[62:63] op_sel_hi:[1,0]
	v_pk_mul_f32 v[134:135], v[86:87], s[62:63] op_sel_hi:[1,0]
	s_waitcnt vmcnt(24)
	v_pk_mul_f32 v[136:137], v[92:93], s[62:63] op_sel_hi:[1,0]
	v_pk_mul_f32 v[138:139], v[90:91], s[62:63] op_sel_hi:[1,0]
	s_branch .LBB0_456
; __device__ __forceinline__ unsigned cvt_pk_bf16(float lo, float hi) { unsigned r; asm volatile("v_cvt_pk_bf16_f32 %0, %1, %2" : "=v"(r) : "v"(lo), "v"(hi)); return r; }
; __device__ __forceinline__ float bf_lo(unsigned w) { return __uint_as_float(w << 16); }
; __device__ __forceinline__ float bf_hi(unsigned w) { return __uint_as_float(w & 0xffff0000u); }
; __device__ __forceinline__ float fast_rcp(float x) { return __builtin_amdgcn_rcpf(x); }
; __device__ __forceinline__ void lru_fused(const bf16* XC, const bf16* Wrg_t, const bf16* PROJ, bf16* YL, const float* b_a, const float* b_x, const float* sp8,
;                                           LAS unsigned char* lds, int tid, int lane, int wave, int vcu, int G) {
;     ...
;             for (int r2 = 0; r2 < 2; ++r2) { const size_t ro = (row0 + 16 * r2 + fr) * D;
; #pragma unroll
;                 for (int c2 = 0; c2 < 2; ++c2) { const v2u gw = gq[r2][c2]; const float gg[4] = {bf_lo(gw.x), bf_hi(gw.x), bf_lo(gw.y), bf_hi(gw.y)}; float y[4];
; #pragma unroll
;                     for (int j = 0; j < 4; ++j) { const float hh = U[r2][c2][j] + A[r2][c2][j] * hin[c2][j]; const float gx = gg[j], gz = gx * __builtin_fmaf(gx * gx, -0.10294324f, -2.30220819f);
;                         y[j] = hh * gx * pg8::fast_rcp(1.0f + __builtin_amdgcn_exp2f(gz)); }
;                     v2u o; o.x = cvt_pk_bf16(y[0], y[1]); o.y = cvt_pk_bf16(y[2], y[3]); *(v2u*)(obase + ro + 16 * c2) = o; } }
; #pragma unroll
;             for (int r2 = 0; r2 < 2; ++r2)
; #pragma unroll
;                 for (int c2 = 0; c2 < 2; ++c2) { xq[r2][c2] = xqn[r2][c2]; gq[r2][c2] = gqn[r2][c2]; }
.LBB0_455:
	s_or_b64 exec, exec, s[66:67]
	v_lshlrev_b32_e32 v3, 16, v158
	s_waitcnt lgkmcnt(0)
	v_fmac_f32_e32 v175, v173, v106
	v_mul_f32_e32 v173, v3, v3
	v_fmamk_f32 v173, v173, 0xbdd2d3e8, v171
	v_mul_f32_e32 v173, v173, v3
	v_exp_f32_e32 v173, v173
	v_and_b32_e32 v158, 0xffff0000, v158
	v_lshlrev_b32_e32 v192, 16, v159
	v_and_b32_e32 v159, 0xffff0000, v159
	v_add_f32_e32 v173, 1.0, v173
	v_rcp_f32_e32 v173, v173
	v_mul_f32_e32 v193, v158, v158
	v_mul_f32_e32 v3, v175, v3
	v_fmac_f32_e32 v177, v174, v107
	v_mul_f32_e32 v174, v159, v159
	v_fmamk_f32 v193, v193, 0xbdd2d3e8, v171
	v_mul_f32_e32 v3, v173, v3
	v_mul_f32_e32 v173, v192, v192
	v_fmamk_f32 v174, v174, 0xbdd2d3e8, v171
	v_mul_f32_e32 v193, v193, v158
	v_fmamk_f32 v173, v173, 0xbdd2d3e8, v171
	v_mul_f32_e32 v174, v174, v159
	v_exp_f32_e32 v193, v193
	v_mul_f32_e32 v173, v173, v192
	v_exp_f32_e32 v174, v174
	v_exp_f32_e32 v173, v173
	v_add_f32_e32 v175, 1.0, v193
	v_rcp_f32_e32 v175, v175
	v_add_f32_e32 v174, 1.0, v174
	v_add_f32_e32 v173, 1.0, v173
	v_rcp_f32_e32 v174, v174
	v_rcp_f32_e32 v173, v173
	v_fmac_f32_e32 v182, v176, v109
	v_lshl_add_u64 v[4:5], v[130:131], 0, s[64:65]
	v_mul_f32_e32 v158, v177, v158
	v_fmac_f32_e32 v184, v181, v108
	v_mul_f32_e32 v159, v182, v159
	v_mul_f32_e32 v158, v175, v158
	v_mul_f32_e32 v175, v184, v192
	v_mul_f32_e32 v159, v174, v159
	v_add_co_u32_e32 v4, vcc, s17, v4
	v_mul_f32_e32 v173, v173, v175
	v_cvt_pk_bf16_f32 v252, v3, v158
	v_cvt_pk_bf16_f32 v253, v173, v159
	s_nop 0
	v_addc_co_u32_e32 v5, vcc, 0, v5, vcc
	v_lshlrev_b32_e32 v3, 16, v152
	v_and_b32_e32 v152, 0xffff0000, v152
	v_mul_f32_e32 v159, v3, v3
	v_mul_f32_e32 v173, v152, v152
	v_fmamk_f32 v159, v159, 0xbdd2d3e8, v171
	v_fmamk_f32 v173, v173, 0xbdd2d3e8, v171
	v_mul_f32_e32 v159, v159, v3
	v_mul_f32_e32 v173, v173, v152
	v_exp_f32_e32 v159, v159
	v_exp_f32_e32 v173, v173
	v_fmac_f32_e32 v186, v183, v102
	v_fmac_f32_e32 v188, v185, v103
	v_add_f32_e32 v159, 1.0, v159
	v_add_f32_e32 v173, 1.0, v173
	v_rcp_f32_e32 v159, v159
	v_rcp_f32_e32 v173, v173
	v_lshlrev_b32_e32 v158, 16, v153
	v_and_b32_e32 v153, 0xffff0000, v153
	v_mul_f32_e32 v3, v186, v3
	v_mul_f32_e32 v152, v188, v152
	v_mul_f32_e32 v3, v159, v3
	v_mul_f32_e32 v152, v173, v152
	v_mul_f32_e32 v173, v153, v153
	v_mul_f32_e32 v159, v158, v158
	v_fmamk_f32 v173, v173, 0xbdd2d3e8, v171
	v_cvt_pk_bf16_f32 v254, v3, v152
	v_lshlrev_b32_e32 v3, 16, v146
	v_and_b32_e32 v146, 0xffff0000, v146
	v_fmamk_f32 v159, v159, 0xbdd2d3e8, v171
	v_mul_f32_e32 v173, v173, v153
	v_fma_f32 v94, v98, v106, v94
	v_mul_f32_e32 v106, v146, v146
	v_mul_f32_e32 v159, v159, v158
	v_exp_f32_e32 v173, v173
	v_mul_f32_e32 v98, v3, v3
	v_fmamk_f32 v106, v106, 0xbdd2d3e8, v171
	v_exp_f32_e32 v159, v159
	v_fmamk_f32 v98, v98, 0xbdd2d3e8, v171
	v_mul_f32_e32 v106, v106, v146
	v_mul_f32_e32 v98, v98, v3
	v_exp_f32_e32 v106, v106
	v_exp_f32_e32 v98, v98
	v_add_f32_e32 v173, 1.0, v173
	v_add_f32_e32 v159, 1.0, v159
	v_rcp_f32_e32 v173, v173
	v_rcp_f32_e32 v159, v159
	v_mul_f32_e32 v3, v94, v3
	v_add_f32_e32 v94, 1.0, v106
	v_fmac_f32_e32 v190, v187, v105
	v_add_f32_e32 v98, 1.0, v98
	v_rcp_f32_e32 v94, v94
	v_fmac_f32_e32 v191, v189, v104
	v_mul_f32_e32 v153, v190, v153
	v_rcp_f32_e32 v98, v98
	v_mul_f32_e32 v158, v191, v158
	v_mul_f32_e32 v153, v173, v153
	v_fmac_f32_e32 v95, v99, v107
	v_mul_f32_e32 v158, v159, v158
	v_cvt_pk_bf16_f32 v255, v158, v153
	global_store_dwordx4 v[4:5], v[252:255], off
	v_lshlrev_b32_e32 v152, 16, v147
	v_mul_f32_e32 v95, v95, v146
	v_and_b32_e32 v147, 0xffff0000, v147
	v_mul_f32_e32 v94, v94, v95
	v_fma_f32 v95, v100, v108, v96
	v_mul_f32_e32 v96, v152, v152
	v_mul_f32_e32 v3, v98, v3
	v_fmamk_f32 v96, v96, 0xbdd2d3e8, v171
	v_mul_f32_e32 v98, v147, v147
	v_mul_f32_e32 v96, v96, v152
	v_fmamk_f32 v98, v98, 0xbdd2d3e8, v171
	v_exp_f32_e32 v96, v96
	v_mul_f32_e32 v98, v98, v147
	v_exp_f32_e32 v98, v98
	v_lshl_add_u64 v[4:5], v[128:129], 0, s[64:65]
	v_add_f32_e32 v96, 1.0, v96
	v_rcp_f32_e32 v96, v96
	v_add_f32_e32 v98, 1.0, v98
	v_rcp_f32_e32 v98, v98
	v_mul_f32_e32 v95, v95, v152
	v_fmac_f32_e32 v97, v101, v109
	v_add_co_u32_e32 v4, vcc, s17, v4
	v_mul_f32_e32 v95, v96, v95
	v_mul_f32_e32 v96, v97, v147
	v_cvt_pk_bf16_f32 v252, v3, v94
	v_addc_co_u32_e32 v5, vcc, 0, v5, vcc
	v_mul_f32_e32 v96, v98, v96
	v_cvt_pk_bf16_f32 v253, v95, v96
	s_waitcnt vmcnt(27)
	v_and_b32_e32 v94, 0xffff0000, v140
	v_lshlrev_b32_e32 v3, 16, v140
	v_mul_f32_e32 v97, v94, v94
	v_fma_f32 v86, v90, v102, v86
	v_mul_f32_e32 v90, v3, v3
	v_fmamk_f32 v97, v97, 0xbdd2d3e8, v171
	v_fmamk_f32 v90, v90, 0xbdd2d3e8, v171
	v_mul_f32_e32 v97, v97, v94
	v_mul_f32_e32 v90, v90, v3
	v_exp_f32_e32 v97, v97
	v_exp_f32_e32 v90, v90
	v_mul_f32_e32 v3, v86, v3
	v_fmac_f32_e32 v87, v91, v103
	v_add_f32_e32 v86, 1.0, v97
	v_add_f32_e32 v90, 1.0, v90
	v_rcp_f32_e32 v86, v86
	v_rcp_f32_e32 v90, v90
	v_lshlrev_b32_e32 v95, 16, v141
	v_mul_f32_e32 v87, v87, v94
	v_and_b32_e32 v96, 0xffff0000, v141
	v_mul_f32_e32 v86, v86, v87
	v_fma_f32 v87, v92, v104, v88
	v_mul_f32_e32 v88, v95, v95
	v_mul_f32_e32 v3, v90, v3
	v_fmamk_f32 v88, v88, 0xbdd2d3e8, v171
	v_mul_f32_e32 v90, v96, v96
	v_mul_f32_e32 v88, v88, v95
	v_fmamk_f32 v90, v90, 0xbdd2d3e8, v171
	v_exp_f32_e32 v88, v88
	v_mul_f32_e32 v90, v90, v96
	v_exp_f32_e32 v90, v90
	s_add_u32 s64, s64, 0x200000
	v_add_f32_e32 v88, 1.0, v88
	v_rcp_f32_e32 v88, v88
	v_add_f32_e32 v90, 1.0, v90
	v_rcp_f32_e32 v90, v90
	s_addc_u32 s65, s65, 0
	s_add_u32 s19, s19, 0x100
	v_mul_f32_e32 v87, v87, v95
	v_fmac_f32_e32 v89, v93, v105
	s_addc_u32 s20, s20, 0
	s_add_i32 s21, s21, 32
	s_add_i32 s22, s22, 1
	v_mul_f32_e32 v87, v88, v87
	v_mul_f32_e32 v88, v89, v96
	s_cmp_eq_u32 s64, 0x4000000
	s_waitcnt vmcnt(1)
	v_mov_b64_e32 v[140:141], v[162:163]
	v_mov_b64_e32 v[146:147], v[160:161]
	v_mov_b64_e32 v[152:153], v[156:157]
	v_mov_b64_e32 v[158:159], v[154:155]
	v_mul_f32_e32 v88, v90, v88
	v_cvt_pk_bf16_f32 v254, v3, v86
	v_cvt_pk_bf16_f32 v255, v87, v88
	global_store_dwordx4 v[4:5], v[252:255], off
	s_cbranch_scc1 .LBB0_453
; __device__ __forceinline__ float bf_lo(unsigned w) { return __uint_as_float(w << 16); }
; __device__ __forceinline__ float bf_hi(unsigned w) { return __uint_as_float(w & 0xffff0000u); }
; #define LAS __attribute__((address_space(3)))
; __device__ __forceinline__ void lru_fused(const bf16* XC, const bf16* Wrg_t, const bf16* PROJ, bf16* YL, const float* b_a, const float* b_x, const float* sp8,
;                                           LAS unsigned char* lds, int tid, int lane, int wave, int vcu, int G) {
;     ...
;                 bf16x8 bq[2][4];
; #pragma unroll
;                 for (int cb = 0; cb < 4; ++cb) bq[0][cb] = *(const LAS bf16x8*)(bl + cb * 16 * RG_PITCH);
; #pragma unroll
;                 for (int kb = 0; kb < 8; ++kb) {
;                     if (kb + 1 < 8) {
; #pragma unroll
;                         for (int cb = 0; cb < 4; ++cb) bq[(kb + 1) & 1][cb] = *(const LAS bf16x8*)(bl + cb * 16 * RG_PITCH + (kb + 1) * 64); }
;                     __builtin_amdgcn_sched_barrier(0);
; #pragma unroll
;                     for (int cb = 0; cb < 4; ++cb)
; #pragma unroll
;                         for (int r2 = 0; r2 < 2; ++r2) acc[r2][cb] = __builtin_amdgcn_mfma_f32_16x16x32_bf16(bq[kb & 1][cb], af[r2][kb], acc[r2][cb], 0, 0, 0);
;     ...
;                 for (int c2 = 0; c2 < 2; ++c2) { const f32x4 rp = acc[r2][c2] + ba[c2], ip = acc[r2][c2 + 2] + bx[c2]; const v2u xw = xq[r2][c2];
;                     const float xv[4] = {bf_lo(xw.x), bf_hi(xw.x), bf_lo(xw.y), bf_hi(xw.y)};
.LBB0_456:
	ds_read_b128 v[86:89], v170
	ds_read_b128 v[90:93], v170 offset:64
	ds_read_b128 v[94:97], v170 offset:2176
	ds_read_b128 v[98:101], v170 offset:2240
	ds_read_b128 v[106:109], v170 offset:17408
	ds_read_b128 v[154:157], v170 offset:17472
	ds_read_b128 v[160:163], v170 offset:19584
	ds_read_b128 v[174:177], v170 offset:19648
	s_waitcnt vmcnt(15)
	s_waitcnt vmcnt(12)
	s_waitcnt vmcnt(3)
	s_waitcnt vmcnt(1)
	s_bfe_u32 s68, s18, 0x30001
	s_cmp_lt_u32 s68, 4
	s_cbranch_scc0 .Lxq_4567
	s_cmp_lt_u32 s68, 2
	s_cbranch_scc0 .Lxq_23
	s_cmp_eq_u32 s68, 0
	s_cbranch_scc0 .Lxq_1
	v_mov_b64_e32 v[198:199], v[70:71]
	v_mov_b64_e32 v[104:105], v[72:73]
	v_mov_b64_e32 v[102:103], v[82:83]
	v_mov_b64_e32 v[4:5], v[84:85]
	s_branch .Lxq_done
.Lxq_1:
	v_mov_b64_e32 v[198:199], v[62:63]
	v_mov_b64_e32 v[104:105], v[64:65]
	v_mov_b64_e32 v[102:103], v[78:79]
	v_mov_b64_e32 v[4:5], v[80:81]
	s_branch .Lxq_done
.Lxq_23:
	s_cmp_eq_u32 s68, 2
	s_cbranch_scc0 .Lxq_3
	v_mov_b64_e32 v[198:199], v[54:55]
	v_mov_b64_e32 v[104:105], v[56:57]
	v_mov_b64_e32 v[102:103], v[74:75]
	v_mov_b64_e32 v[4:5], v[76:77]
	s_branch .Lxq_done
.Lxq_3:
	v_mov_b64_e32 v[198:199], v[46:47]
	v_mov_b64_e32 v[104:105], v[48:49]
	v_mov_b64_e32 v[102:103], v[66:67]
	v_mov_b64_e32 v[4:5], v[68:69]
	s_branch .Lxq_done
.Lxq_4567:
	s_cmp_lt_u32 s68, 6
	s_cbranch_scc0 .Lxq_67
	s_cmp_eq_u32 s68, 4
	s_cbranch_scc0 .Lxq_5
	v_mov_b64_e32 v[198:199], v[34:35]
	v_mov_b64_e32 v[104:105], v[36:37]
	v_mov_b64_e32 v[102:103], v[58:59]
	v_mov_b64_e32 v[4:5], v[60:61]
	s_branch .Lxq_done
.Lxq_5:
	v_mov_b64_e32 v[198:199], v[30:31]
	v_mov_b64_e32 v[104:105], v[32:33]
	v_mov_b64_e32 v[102:103], v[50:51]
	v_mov_b64_e32 v[4:5], v[52:53]
	s_branch .Lxq_done
.Lxq_67:
	s_cmp_eq_u32 s68, 6
	s_cbranch_scc0 .Lxq_7
	v_mov_b64_e32 v[198:199], v[26:27]
	v_mov_b64_e32 v[104:105], v[28:29]
	v_mov_b64_e32 v[102:103], v[42:43]
	v_mov_b64_e32 v[4:5], v[44:45]
	s_branch .Lxq_done
.Lxq_7:
	v_mov_b64_e32 v[198:199], v[22:23]
	v_mov_b64_e32 v[104:105], v[24:25]
	v_mov_b64_e32 v[102:103], v[38:39]
	v_mov_b64_e32 v[4:5], v[40:41]
.Lxq_done:
	s_waitcnt lgkmcnt(7)
	v_mfma_f32_16x16x32_bf16 v[142:145], v[86:89], v[70:73], 0
	v_mfma_f32_16x16x32_bf16 v[86:89], v[86:89], v[82:85], 0
	s_waitcnt lgkmcnt(5)
	v_mfma_f32_16x16x32_bf16 v[148:151], v[94:97], v[70:73], 0
	v_mfma_f32_16x16x32_bf16 v[94:97], v[94:97], v[82:85], 0
	s_waitcnt lgkmcnt(3)
	v_mfma_f32_16x16x32_bf16 v[182:185], v[106:109], v[70:73], 0
	v_mfma_f32_16x16x32_bf16 v[106:109], v[106:109], v[82:85], 0
	s_waitcnt lgkmcnt(1)
	v_mfma_f32_16x16x32_bf16 v[70:73], v[160:163], v[70:73], 0
	v_mfma_f32_16x16x32_bf16 v[82:85], v[160:163], v[82:85], 0
	ds_read_b128 v[160:163], v170 offset:128
	ds_read_b128 v[186:189], v170 offset:2304
	ds_read_b128 v[190:193], v170 offset:17536
	ds_read_b128 v[194:197], v170 offset:19712
	v_mfma_f32_16x16x32_bf16 v[142:145], v[90:93], v[62:65], v[142:145]
	v_mfma_f32_16x16x32_bf16 v[86:89], v[90:93], v[78:81], v[86:89]
	v_mfma_f32_16x16x32_bf16 v[90:93], v[98:101], v[62:65], v[148:151]
	v_mfma_f32_16x16x32_bf16 v[94:97], v[98:101], v[78:81], v[94:97]
	v_mfma_f32_16x16x32_bf16 v[98:101], v[154:157], v[62:65], v[182:185]
	s_waitcnt lgkmcnt(4)
	v_mfma_f32_16x16x32_bf16 v[62:65], v[174:177], v[62:65], v[70:73]
	v_mfma_f32_16x16x32_bf16 v[70:73], v[174:177], v[78:81], v[82:85]
	v_mfma_f32_16x16x32_bf16 v[106:109], v[154:157], v[78:81], v[106:109]
	ds_read_b128 v[78:81], v170 offset:192
	s_nop 0
	ds_read_b128 v[82:85], v170 offset:2368
	ds_read_b128 v[148:151], v170 offset:17600
	ds_read_b128 v[154:157], v170 offset:19776
	s_waitcnt lgkmcnt(7)
	v_mfma_f32_16x16x32_bf16 v[142:145], v[160:163], v[54:57], v[142:145]
	v_mfma_f32_16x16x32_bf16 v[86:89], v[160:163], v[74:77], v[86:89]
	s_waitcnt lgkmcnt(6)
	v_mfma_f32_16x16x32_bf16 v[90:93], v[186:189], v[54:57], v[90:93]
	v_mfma_f32_16x16x32_bf16 v[94:97], v[186:189], v[74:77], v[94:97]
	s_waitcnt lgkmcnt(5)
	v_mfma_f32_16x16x32_bf16 v[98:101], v[190:193], v[54:57], v[98:101]
	s_waitcnt lgkmcnt(4)
	v_mfma_f32_16x16x32_bf16 v[54:57], v[194:197], v[54:57], v[62:65]
	v_mfma_f32_16x16x32_bf16 v[62:65], v[194:197], v[74:77], v[70:73]
	v_mfma_f32_16x16x32_bf16 v[106:109], v[190:193], v[74:77], v[106:109]
	s_nop 1
	ds_read_b128 v[70:73], v170 offset:256
	ds_read_b128 v[74:77], v170 offset:2432
	ds_read_b128 v[160:163], v170 offset:17664
	ds_read_b128 v[174:177], v170 offset:19840
	s_waitcnt lgkmcnt(7)
	v_mfma_f32_16x16x32_bf16 v[142:145], v[78:81], v[46:49], v[142:145]
	v_mfma_f32_16x16x32_bf16 v[78:81], v[78:81], v[66:69], v[86:89]
	s_waitcnt lgkmcnt(6)
	v_mfma_f32_16x16x32_bf16 v[86:89], v[82:85], v[46:49], v[90:93]
	v_mfma_f32_16x16x32_bf16 v[82:85], v[82:85], v[66:69], v[94:97]
	s_waitcnt lgkmcnt(5)
	v_mfma_f32_16x16x32_bf16 v[90:93], v[148:151], v[46:49], v[98:101]
	v_mfma_f32_16x16x32_bf16 v[94:97], v[148:151], v[66:69], v[106:109]
	s_waitcnt lgkmcnt(4)
	v_mfma_f32_16x16x32_bf16 v[46:49], v[154:157], v[46:49], v[54:57]
	v_mfma_f32_16x16x32_bf16 v[54:57], v[154:157], v[66:69], v[62:65]
	s_nop 2
	ds_read_b128 v[62:65], v170 offset:320
	ds_read_b128 v[66:69], v170 offset:2496
	ds_read_b128 v[98:101], v170 offset:17728
	ds_read_b128 v[106:109], v170 offset:19904
	s_waitcnt lgkmcnt(7)
	v_mfma_f32_16x16x32_bf16 v[142:145], v[70:73], v[34:37], v[142:145]
	v_mfma_f32_16x16x32_bf16 v[70:73], v[70:73], v[58:61], v[78:81]
	s_waitcnt lgkmcnt(6)
	v_mfma_f32_16x16x32_bf16 v[78:81], v[74:77], v[34:37], v[86:89]
	v_mfma_f32_16x16x32_bf16 v[74:77], v[74:77], v[58:61], v[82:85]
	s_waitcnt lgkmcnt(5)
	v_mfma_f32_16x16x32_bf16 v[82:85], v[160:163], v[34:37], v[90:93]
	v_mfma_f32_16x16x32_bf16 v[86:89], v[160:163], v[58:61], v[94:97]
	s_waitcnt lgkmcnt(4)
; __device__ __forceinline__ float bf_lo(unsigned w) { return __uint_as_float(w << 16); }
; #define LAS __attribute__((address_space(3)))
; __device__ __forceinline__ void lru_fused(const bf16* XC, const bf16* Wrg_t, const bf16* PROJ, bf16* YL, const float* b_a, const float* b_x, const float* sp8,
;                                           LAS unsigned char* lds, int tid, int lane, int wave, int vcu, int G) {
;     ...
;                 for (int kb = 0; kb < 8; ++kb) {
;                     if (kb + 1 < 8) {
; #pragma unroll
;                         for (int cb = 0; cb < 4; ++cb) bq[(kb + 1) & 1][cb] = *(const LAS bf16x8*)(bl + cb * 16 * RG_PITCH + (kb + 1) * 64); }
;                     __builtin_amdgcn_sched_barrier(0);
; #pragma unroll
;                     for (int cb = 0; cb < 4; ++cb)
; #pragma unroll
;                         for (int r2 = 0; r2 < 2; ++r2) acc[r2][cb] = __builtin_amdgcn_mfma_f32_16x16x32_bf16(bq[kb & 1][cb], af[r2][kb], acc[r2][cb], 0, 0, 0);
;                     __builtin_amdgcn_sched_barrier(0);
;                 }
;             }
;             v2u xqn[2][2], gqn[2][2];
;             { const size_t rown = (i + 1 < SEQ / 256) ? row0 + 256 : row0;
; #pragma unroll
;                 for (int r2 = 0; r2 < 2; ++r2) { const size_t ro = (rown + 16 * r2 + fr) * D, rg = (rown + 16 * r2 + fr) * NIN;
; #pragma unroll
;                     for (int kb = 0; kb < 8; ++kb) af[r2][kb] = *(const bf16x8*)(abase + ro + 32 * kb);
; #pragma unroll
;                     for (int c2 = 0; c2 < 2; ++c2) { xqn[r2][c2] = *(const v2u*)(xbase + ro + 16 * c2); gqn[r2][c2] = *(const v2u*)(gbase + rg + 16 * c2); } } }
;             float A[2][2][4], U[2][2][4];
; #pragma unroll
;             for (int r2 = 0; r2 < 2; ++r2)
; #pragma unroll
;                 for (int c2 = 0; c2 < 2; ++c2) { const f32x4 rp = acc[r2][c2] + ba[c2], ip = acc[r2][c2 + 2] + bx[c2]; const v2u xw = xq[r2][c2];
;                     const float xv[4] = {bf_lo(xw.x), bf_hi(xw.x), bf_lo(xw.y), bf_hi(xw.y)};
; #pragma unroll
;                     for (int j = 0; j < 4; ++j) { const float r = pg8::sigmoidf_(rp[j]), ig = pg8::sigmoidf_(ip[j]);
;                         const float av = __builtin_amdgcn_exp2f(sp[c2][j] * r);
;                         A[r2][c2][j] = av; U[r2][c2][j] = __builtin_amdgcn_sqrtf(fmaxf(__builtin_fmaf(-av, av, 1.0f), 0.0f)) * (ig * xv[j]); } }
	v_mfma_f32_16x16x32_bf16 v[34:37], v[174:177], v[34:37], v[46:49]
	v_mfma_f32_16x16x32_bf16 v[46:49], v[174:177], v[58:61], v[54:57]
	s_nop 2
	ds_read_b128 v[54:57], v170 offset:384
	ds_read_b128 v[58:61], v170 offset:2560
	ds_read_b128 v[90:93], v170 offset:17792
	ds_read_b128 v[94:97], v170 offset:19968
	s_waitcnt lgkmcnt(7)
	v_mfma_f32_16x16x32_bf16 v[142:145], v[62:65], v[30:33], v[142:145]
	v_mfma_f32_16x16x32_bf16 v[62:65], v[62:65], v[50:53], v[70:73]
	s_waitcnt lgkmcnt(6)
	v_mfma_f32_16x16x32_bf16 v[70:73], v[66:69], v[30:33], v[78:81]
	v_mfma_f32_16x16x32_bf16 v[66:69], v[66:69], v[50:53], v[74:77]
	s_waitcnt lgkmcnt(5)
	v_mfma_f32_16x16x32_bf16 v[74:77], v[98:101], v[30:33], v[82:85]
	v_mfma_f32_16x16x32_bf16 v[78:81], v[98:101], v[50:53], v[86:89]
	s_waitcnt lgkmcnt(4)
	v_mfma_f32_16x16x32_bf16 v[30:33], v[106:109], v[30:33], v[34:37]
	v_mfma_f32_16x16x32_bf16 v[34:37], v[106:109], v[50:53], v[46:49]
	s_nop 2
	ds_read_b128 v[46:49], v170 offset:448
	ds_read_b128 v[50:53], v170 offset:2624
	ds_read_b128 v[82:85], v170 offset:17856
	ds_read_b128 v[86:89], v170 offset:20032
	s_waitcnt lgkmcnt(7)
	v_mfma_f32_16x16x32_bf16 v[98:101], v[54:57], v[26:29], v[142:145]
	v_mfma_f32_16x16x32_bf16 v[54:57], v[54:57], v[42:45], v[62:65]
	s_waitcnt lgkmcnt(6)
	v_mfma_f32_16x16x32_bf16 v[62:65], v[58:61], v[26:29], v[70:73]
	v_mfma_f32_16x16x32_bf16 v[58:61], v[58:61], v[42:45], v[66:69]
	s_waitcnt lgkmcnt(5)
	v_mfma_f32_16x16x32_bf16 v[66:69], v[90:93], v[26:29], v[74:77]
	v_mfma_f32_16x16x32_bf16 v[70:73], v[90:93], v[42:45], v[78:81]
	s_waitcnt lgkmcnt(4)
	v_mfma_f32_16x16x32_bf16 v[26:29], v[94:97], v[26:29], v[30:33]
	v_mfma_f32_16x16x32_bf16 v[30:33], v[94:97], v[42:45], v[34:37]
	s_waitcnt lgkmcnt(3)
	v_mfma_f32_16x16x32_bf16 v[106:109], v[46:49], v[22:25], v[98:101]
	v_mfma_f32_16x16x32_bf16 v[98:101], v[46:49], v[38:41], v[54:57]
	s_waitcnt lgkmcnt(2)
	v_mfma_f32_16x16x32_bf16 v[188:191], v[50:53], v[22:25], v[62:65]
	v_mfma_f32_16x16x32_bf16 v[90:93], v[50:53], v[38:41], v[58:61]
	s_waitcnt lgkmcnt(1)
	v_mfma_f32_16x16x32_bf16 v[182:185], v[82:85], v[22:25], v[66:69]
	v_mfma_f32_16x16x32_bf16 v[94:97], v[82:85], v[38:41], v[70:73]
	s_waitcnt lgkmcnt(0)
	v_mfma_f32_16x16x32_bf16 v[192:195], v[86:89], v[22:25], v[26:29]
	v_mfma_f32_16x16x32_bf16 v[86:89], v[86:89], v[38:41], v[30:33]
	v_add_f32_e32 v3, v6, v106
	v_mul_f32_e32 v3, 0xbfb8aa3b, v3
	v_exp_f32_e32 v3, v3
	s_add_u32 s23, s19, 0xffffff00
	s_addc_u32 s24, s20, -1
	s_cmp_eq_u32 s64, 0x3e00000
	s_cselect_b32 s25, s24, s20
	s_cselect_b32 s24, s23, s19
	v_mov_b32_e32 v39, s25
	v_or_b32_e32 v38, s24, v110
	v_lshlrev_b64 v[40:41], 13, v[38:39]
	v_mad_u64_u32 v[38:39], s[26:27], v38, s13, v[126:127]
	s_mul_i32 s23, s25, 0xa000
	v_lshl_add_u64 v[22:23], v[122:123], 0, v[40:41]
	v_lshl_add_u64 v[40:41], v[124:125], 0, v[40:41]
	v_add_u32_e32 v39, s23, v39
	global_load_dwordx4 v[70:73], v[22:23], off
	s_nop 0
	v_add_f32_e32 v173, v14, v182
	v_mul_f32_e32 v173, 0xbfb8aa3b, v173
	v_exp_f32_e32 v174, v173
	v_add_f32_e32 v3, 1.0, v3
	v_rcp_f32_e32 v3, v3
	v_add_f32_e32 v107, v7, v107
	v_add_f32_e32 v174, 1.0, v174
	v_mul_f32_e32 v107, 0xbfb8aa3b, v107
	v_mul_f32_e32 v3, v134, v3
	v_exp_f32_e32 v173, v3
	v_rcp_f32_e32 v174, v174
	v_exp_f32_e32 v107, v107
	v_lshlrev_b32_e32 v106, 16, v198
	v_fma_f32 v175, -v173, v173, 1.0
	global_load_dwordx4 v[62:65], v[22:23], off offset:64
	v_mul_f32_e32 v106, v174, v106
	v_add_f32_e32 v174, v15, v183
	v_add_f32_e32 v107, 1.0, v107
	v_max_f32_e32 v175, 0, v175
	v_mul_f32_e32 v174, 0xbfb8aa3b, v174
	v_rcp_f32_e32 v107, v107
	v_sqrt_f32_e32 v175, v175
	v_exp_f32_e32 v174, v174
	v_add_f32_e32 v177, v16, v184
	v_mul_f32_e32 v107, v135, v107
	v_mul_f32_e32 v175, v106, v175
	v_add_f32_e32 v106, 1.0, v174
	v_exp_f32_e32 v174, v107
	v_add_f32_e32 v107, v8, v108
	v_mul_f32_e32 v107, 0xbfb8aa3b, v107
	v_exp_f32_e32 v107, v107
	global_load_dwordx4 v[54:57], v[22:23], off offset:128
	v_fma_f32 v108, -v174, v174, 1.0
	v_rcp_f32_e32 v106, v106
	v_max_f32_e32 v108, 0, v108
	v_add_f32_e32 v107, 1.0, v107
	v_mul_f32_e32 v177, 0xbfb8aa3b, v177
	v_rcp_f32_e32 v107, v107
	v_sqrt_f32_e32 v108, v108
	v_exp_f32_e32 v181, v177
	v_and_b32_e32 v176, 0xffff0000, v198
	v_mul_f32_e32 v106, v106, v176
	v_mul_f32_e32 v107, v132, v107
	v_mul_f32_e32 v177, v106, v108
	v_add_f32_e32 v106, 1.0, v181
	v_exp_f32_e32 v181, v107
	v_add_f32_e32 v107, v9, v109
	global_load_dwordx4 v[46:49], v[22:23], off offset:192
	v_mul_f32_e32 v107, 0xbfb8aa3b, v107
	v_exp_f32_e32 v107, v107
	v_add_f32_e32 v109, v17, v185
	v_mul_f32_e32 v109, 0xbfb8aa3b, v109
	v_exp_f32_e32 v109, v109
	v_add_f32_e32 v107, 1.0, v107
	v_rcp_f32_e32 v107, v107
	v_fma_f32 v108, -v181, v181, 1.0
	v_max_f32_e32 v108, 0, v108
	v_and_b32_e32 v3, 0xffff0000, v199
	v_mul_f32_e32 v107, v133, v107
	v_exp_f32_e32 v176, v107
	v_sqrt_f32_e32 v107, v108
	v_add_f32_e32 v108, 1.0, v109
	v_rcp_f32_e32 v108, v108
	global_load_dwordx4 v[34:37], v[22:23], off offset:256
	v_fma_f32 v109, -v176, v176, 1.0
	v_max_f32_e32 v109, 0, v109
	v_sqrt_f32_e32 v109, v109
	v_mul_f32_e32 v3, v108, v3
	v_add_f32_e32 v108, v18, v192
	v_rcp_f32_e32 v106, v106
	v_mul_f32_e32 v182, v3, v109
	v_add_f32_e32 v3, v10, v188
	v_mul_f32_e32 v3, 0xbfb8aa3b, v3
	v_exp_f32_e32 v3, v3
	v_mul_f32_e32 v108, 0xbfb8aa3b, v108
	v_exp_f32_e32 v108, v108
	v_lshlrev_b32_e32 v186, 16, v199
	v_add_f32_e32 v3, 1.0, v3
	v_rcp_f32_e32 v3, v3
	v_mul_f32_e32 v106, v106, v186
	global_load_dwordx4 v[30:33], v[22:23], off offset:320
	v_mul_f32_e32 v184, v106, v107
	v_lshlrev_b32_e32 v107, 16, v105
	v_mul_f32_e32 v3, v138, v3
	v_exp_f32_e32 v183, v3
	v_and_b32_e32 v3, 0xffff0000, v105
; __device__ __forceinline__ float bf_lo(unsigned w) { return __uint_as_float(w << 16); }
; __device__ __forceinline__ float bf_hi(unsigned w) { return __uint_as_float(w & 0xffff0000u); }
; __device__ __forceinline__ float sigmoidf_(float x) { return fast_rcp(1.0f + fast_exp(-x)); }
; __device__ __forceinline__ void lru_fused(const bf16* XC, const bf16* Wrg_t, const bf16* PROJ, bf16* YL, const float* b_a, const float* b_x, const float* sp8,
;                                           LAS unsigned char* lds, int tid, int lane, int wave, int vcu, int G) {
;     ...
;             v2u xqn[2][2], gqn[2][2];
;             { const size_t rown = (i + 1 < SEQ / 256) ? row0 + 256 : row0;
; #pragma unroll
;                 for (int r2 = 0; r2 < 2; ++r2) { const size_t ro = (rown + 16 * r2 + fr) * D, rg = (rown + 16 * r2 + fr) * NIN;
; #pragma unroll
;                     for (int kb = 0; kb < 8; ++kb) af[r2][kb] = *(const bf16x8*)(abase + ro + 32 * kb);
; #pragma unroll
;                     for (int c2 = 0; c2 < 2; ++c2) { xqn[r2][c2] = *(const v2u*)(xbase + ro + 16 * c2); gqn[r2][c2] = *(const v2u*)(gbase + rg + 16 * c2); } } }
;             float A[2][2][4], U[2][2][4];
; #pragma unroll
;             for (int r2 = 0; r2 < 2; ++r2)
; #pragma unroll
;                 for (int c2 = 0; c2 < 2; ++c2) { const f32x4 rp = acc[r2][c2] + ba[c2], ip = acc[r2][c2 + 2] + bx[c2]; const v2u xw = xq[r2][c2];
;                     const float xv[4] = {bf_lo(xw.x), bf_hi(xw.x), bf_lo(xw.y), bf_hi(xw.y)};
; #pragma unroll
;                     for (int j = 0; j < 4; ++j) { const float r = pg8::sigmoidf_(rp[j]), ig = pg8::sigmoidf_(ip[j]);
;                         const float av = __builtin_amdgcn_exp2f(sp[c2][j] * r);
;                         A[r2][c2][j] = av; U[r2][c2][j] = __builtin_amdgcn_sqrtf(fmaxf(__builtin_fmaf(-av, av, 1.0f), 0.0f)) * (ig * xv[j]); } }
	v_add_f32_e32 v105, 1.0, v108
	v_rcp_f32_e32 v105, v105
	v_lshlrev_b32_e32 v106, 16, v104
	v_fma_f32 v108, -v183, v183, 1.0
	v_add_f32_e32 v109, v19, v193
	v_mul_f32_e32 v105, v105, v106
	v_add_f32_e32 v106, v11, v189
	v_mul_f32_e32 v106, 0xbfb8aa3b, v106
	v_exp_f32_e32 v106, v106
	v_max_f32_e32 v108, 0, v108
	global_load_dwordx4 v[26:29], v[22:23], off offset:384
	v_mul_f32_e32 v109, 0xbfb8aa3b, v109
	v_sqrt_f32_e32 v108, v108
	v_add_f32_e32 v106, 1.0, v106
	v_rcp_f32_e32 v106, v106
	v_exp_f32_e32 v109, v109
	v_mul_f32_e32 v186, v105, v108
	v_and_b32_e32 v104, 0xffff0000, v104
	v_mul_f32_e32 v106, v139, v106
	v_exp_f32_e32 v185, v106
	v_add_f32_e32 v106, v12, v190
	v_mul_f32_e32 v106, 0xbfb8aa3b, v106
	v_exp_f32_e32 v106, v106
	v_add_f32_e32 v105, 1.0, v109
	v_rcp_f32_e32 v105, v105
	v_fma_f32 v108, -v185, v185, 1.0
	s_nop 0
	global_load_dwordx4 v[22:25], v[22:23], off offset:448
	v_add_f32_e32 v106, 1.0, v106
	v_rcp_f32_e32 v106, v106
	v_mul_f32_e32 v104, v105, v104
	v_max_f32_e32 v108, 0, v108
	v_sqrt_f32_e32 v108, v108
	v_mul_f32_e32 v105, v136, v106
	v_exp_f32_e32 v189, v105
	v_add_f32_e32 v105, v13, v191
	v_mul_f32_e32 v105, 0xbfb8aa3b, v105
	v_exp_f32_e32 v105, v105
	v_mul_f32_e32 v188, v104, v108
	v_add_f32_e32 v108, v21, v195
	v_mul_f32_e32 v108, 0xbfb8aa3b, v108
	v_add_f32_e32 v105, 1.0, v105
	v_rcp_f32_e32 v105, v105
	s_nop 0
	v_exp_f32_e32 v108, v108
	v_fma_f32 v106, -v189, v189, 1.0
	v_max_f32_e32 v106, 0, v106
	v_mul_f32_e32 v105, v137, v105
	v_exp_f32_e32 v187, v105
	v_sqrt_f32_e32 v105, v106
	v_add_f32_e32 v106, 1.0, v108
	v_rcp_f32_e32 v106, v106
	v_fma_f32 v108, -v187, v187, 1.0
	v_max_f32_e32 v108, 0, v108
	v_sqrt_f32_e32 v108, v108
	v_mul_f32_e32 v3, v106, v3
	v_add_f32_e32 v109, v20, v194
	v_mul_f32_e32 v109, 0xbfb8aa3b, v109
	v_mul_f32_e32 v190, v3, v108
	v_add_f32_e32 v3, v6, v98
	v_mul_f32_e32 v3, 0xbfb8aa3b, v3
	v_exp_f32_e32 v3, v3
	v_exp_f32_e32 v109, v109
	v_add_f32_e32 v99, v7, v99
	v_mul_f32_e32 v99, 0xbfb8aa3b, v99
	v_add_f32_e32 v3, 1.0, v3
	v_rcp_f32_e32 v3, v3
	v_exp_f32_e32 v99, v99
	v_add_f32_e32 v104, 1.0, v109
	v_add_f32_e32 v94, v14, v94
	v_rcp_f32_e32 v104, v104
	v_mul_f32_e32 v94, 0xbfb8aa3b, v94
	v_mul_f32_e32 v3, v134, v3
	v_exp_f32_e32 v94, v94
	v_exp_f32_e32 v98, v3
	global_load_dwordx4 v[154:157], v[38:39], off
	v_add_f32_e32 v99, 1.0, v99
	v_add_f32_e32 v101, v9, v101
	v_rcp_f32_e32 v99, v99
	v_mul_f32_e32 v101, 0xbfb8aa3b, v101
	v_exp_f32_e32 v101, v101
	v_mul_f32_e32 v104, v104, v107
	v_mul_f32_e32 v191, v104, v105
	v_lshlrev_b32_e32 v105, 16, v103
	v_and_b32_e32 v3, 0xffff0000, v103
	v_add_f32_e32 v94, 1.0, v94
	v_fma_f32 v103, -v98, v98, 1.0
	v_add_f32_e32 v95, v15, v95
	v_rcp_f32_e32 v94, v94
	v_max_f32_e32 v103, 0, v103
	v_mul_f32_e32 v95, 0xbfb8aa3b, v95
	v_mul_f32_e32 v99, v135, v99
	v_sqrt_f32_e32 v103, v103
	v_exp_f32_e32 v95, v95
	v_exp_f32_e32 v99, v99
	v_add_f32_e32 v100, v8, v100
	v_add_f32_e32 v101, 1.0, v101
	v_mul_f32_e32 v100, 0xbfb8aa3b, v100
	v_rcp_f32_e32 v101, v101
	v_lshlrev_b32_e32 v104, 16, v102
	v_exp_f32_e32 v100, v100
	v_mul_f32_e32 v94, v94, v104
	v_mul_f32_e32 v94, v94, v103
	v_add_f32_e32 v95, 1.0, v95
	v_fma_f32 v103, -v99, v99, 1.0
	v_add_f32_e32 v97, v17, v97
	v_rcp_f32_e32 v95, v95
	v_lshl_add_u64 v[38:39], v[110:111], 0, s[24:25]
	v_lshl_add_u64 v[148:149], v[38:39], 0, 16
	v_lshlrev_b64 v[150:151], 13, v[148:149]
	v_lshl_add_u64 v[38:39], v[122:123], 0, v[150:151]
	global_load_dwordx4 v[82:85], v[38:39], off
	v_max_f32_e32 v103, 0, v103
	v_mul_f32_e32 v97, 0xbfb8aa3b, v97
	v_mul_f32_e32 v101, v133, v101
	v_sqrt_f32_e32 v103, v103
	v_add_f32_e32 v100, 1.0, v100
	v_exp_f32_e32 v97, v97
	v_exp_f32_e32 v101, v101
	v_rcp_f32_e32 v100, v100
	v_and_b32_e32 v102, 0xffff0000, v102
	v_mul_f32_e32 v95, v95, v102
	v_add_f32_e32 v96, v16, v96
	v_mul_f32_e32 v95, v95, v103
	v_add_f32_e32 v97, 1.0, v97
	v_fma_f32 v103, -v101, v101, 1.0
	v_mul_f32_e32 v96, 0xbfb8aa3b, v96
	global_load_dwordx4 v[78:81], v[38:39], off offset:64
	v_mul_f32_e32 v100, v132, v100
	v_rcp_f32_e32 v97, v97
	v_max_f32_e32 v103, 0, v103
	v_exp_f32_e32 v96, v96
	v_exp_f32_e32 v100, v100
	v_sqrt_f32_e32 v103, v103
	v_mul_f32_e32 v3, v97, v3
	v_add_f32_e32 v96, 1.0, v96
	v_fma_f32 v102, -v100, v100, 1.0
	v_mul_f32_e32 v97, v3, v103
	v_add_f32_e32 v3, v10, v90
	v_rcp_f32_e32 v96, v96
	v_max_f32_e32 v102, 0, v102
	v_mul_f32_e32 v3, 0xbfb8aa3b, v3
	v_sqrt_f32_e32 v102, v102
	global_load_dwordx4 v[74:77], v[38:39], off offset:128
	v_exp_f32_e32 v3, v3
	v_mul_f32_e32 v96, v96, v105
	v_lshlrev_b32_e32 v90, 16, v4
	v_mul_f32_e32 v96, v96, v102
	v_and_b32_e32 v102, 0xffff0000, v4
; __device__ __forceinline__ float bf_lo(unsigned w) { return __uint_as_float(w << 16); }
; __device__ __forceinline__ float bf_hi(unsigned w) { return __uint_as_float(w & 0xffff0000u); }
; __device__ __forceinline__ float sigmoidf_(float x) { return fast_rcp(1.0f + fast_exp(-x)); }
; __device__ __forceinline__ void lru_fused(const bf16* XC, const bf16* Wrg_t, const bf16* PROJ, bf16* YL, const float* b_a, const float* b_x, const float* sp8,
;                                           LAS unsigned char* lds, int tid, int lane, int wave, int vcu, int G) {
;     ...
;                 for (int r2 = 0; r2 < 2; ++r2) { const size_t ro = (rown + 16 * r2 + fr) * D, rg = (rown + 16 * r2 + fr) * NIN;
; #pragma unroll
;                     for (int kb = 0; kb < 8; ++kb) af[r2][kb] = *(const bf16x8*)(abase + ro + 32 * kb);
; #pragma unroll
;                     for (int c2 = 0; c2 < 2; ++c2) { xqn[r2][c2] = *(const v2u*)(xbase + ro + 16 * c2); gqn[r2][c2] = *(const v2u*)(gbase + rg + 16 * c2); } } }
;             float A[2][2][4], U[2][2][4];
; #pragma unroll
;             for (int r2 = 0; r2 < 2; ++r2)
; #pragma unroll
;                 for (int c2 = 0; c2 < 2; ++c2) { const f32x4 rp = acc[r2][c2] + ba[c2], ip = acc[r2][c2 + 2] + bx[c2]; const v2u xw = xq[r2][c2];
;                     const float xv[4] = {bf_lo(xw.x), bf_hi(xw.x), bf_lo(xw.y), bf_hi(xw.y)};
; #pragma unroll
;                     for (int j = 0; j < 4; ++j) { const float r = pg8::sigmoidf_(rp[j]), ig = pg8::sigmoidf_(ip[j]);
;                         const float av = __builtin_amdgcn_exp2f(sp[c2][j] * r);
;                         A[r2][c2][j] = av; U[r2][c2][j] = __builtin_amdgcn_sqrtf(fmaxf(__builtin_fmaf(-av, av, 1.0f), 0.0f)) * (ig * xv[j]); } }
;     ...
; #pragma unroll
;             for (int r2 = 0; r2 < 2; ++r2)
; #pragma unroll
;                 for (int c2 = 0; c2 < 2; ++c2)
;                     asm volatile("s_nop 1\n\t" LRU_STEP(1) LRU_STEP(2) LRU_STEP(4) LRU_STEP(8)
;                                  : "+v"(A[r2][c2][0]), "+v"(A[r2][c2][1]), "+v"(A[r2][c2][2]), "+v"(A[r2][c2][3]), "+v"(U[r2][c2][0]), "+v"(U[r2][c2][1]), "+v"(U[r2][c2][2]), "+v"(U[r2][c2][3]));
	v_add_f32_e32 v3, 1.0, v3
	v_add_f32_e32 v4, v18, v86
	v_rcp_f32_e32 v3, v3
	v_mul_f32_e32 v4, 0xbfb8aa3b, v4
	v_exp_f32_e32 v86, v4
	v_lshlrev_b32_e32 v103, 16, v5
	v_mul_f32_e32 v3, v138, v3
	v_exp_f32_e32 v4, v3
	v_and_b32_e32 v3, 0xffff0000, v5
	v_add_f32_e32 v5, 1.0, v86
	v_rcp_f32_e32 v5, v5
	global_load_dwordx4 v[66:69], v[38:39], off offset:192
	v_fma_f32 v86, -v4, v4, 1.0
	v_add_f32_e32 v87, v19, v87
	v_max_f32_e32 v86, 0, v86
	v_mul_f32_e32 v5, v5, v90
	v_add_f32_e32 v90, v11, v91
	v_mul_f32_e32 v90, 0xbfb8aa3b, v90
	v_exp_f32_e32 v90, v90
	v_mul_f32_e32 v87, 0xbfb8aa3b, v87
	v_sqrt_f32_e32 v86, v86
	v_exp_f32_e32 v87, v87
	v_add_f32_e32 v90, 1.0, v90
	v_rcp_f32_e32 v90, v90
	v_mul_f32_e32 v86, v5, v86
	v_add_f32_e32 v5, 1.0, v87
	v_rcp_f32_e32 v87, v5
	global_load_dwordx4 v[58:61], v[38:39], off offset:256
	v_mul_f32_e32 v5, v139, v90
	v_add_f32_e32 v90, v12, v92
	v_mul_f32_e32 v90, 0xbfb8aa3b, v90
	v_exp_f32_e32 v90, v90
	v_exp_f32_e32 v5, v5
	v_add_f32_e32 v88, v20, v88
	v_add_f32_e32 v89, v21, v89
	v_add_f32_e32 v90, 1.0, v90
	v_rcp_f32_e32 v90, v90
	v_fma_f32 v91, -v5, v5, 1.0
	v_max_f32_e32 v91, 0, v91
	v_sqrt_f32_e32 v91, v91
	v_mul_f32_e32 v90, v136, v90
	v_exp_f32_e32 v92, v90
	v_add_f32_e32 v90, v13, v93
	global_load_dwordx4 v[50:53], v[38:39], off offset:320
	v_mul_f32_e32 v90, 0xbfb8aa3b, v90
	v_exp_f32_e32 v90, v90
	v_mul_f32_e32 v88, 0xbfb8aa3b, v88
	v_mul_f32_e32 v89, 0xbfb8aa3b, v89
	v_exp_f32_e32 v88, v88
	v_add_f32_e32 v90, 1.0, v90
	v_rcp_f32_e32 v90, v90
	v_exp_f32_e32 v89, v89
	v_mul_f32_e32 v87, v87, v102
	v_mul_f32_e32 v87, v87, v91
	v_mul_f32_e32 v90, v137, v90
	v_exp_f32_e32 v93, v90
	v_fma_f32 v91, -v92, v92, 1.0
	v_max_f32_e32 v91, 0, v91
	v_add_f32_e32 v88, 1.0, v88
	global_load_dwordx4 v[42:45], v[38:39], off offset:384
	v_sqrt_f32_e32 v90, v91
	v_add_f32_e32 v89, 1.0, v89
	v_fma_f32 v91, -v93, v93, 1.0
	v_rcp_f32_e32 v88, v88
	v_rcp_f32_e32 v89, v89
	v_max_f32_e32 v91, 0, v91
	v_sqrt_f32_e32 v91, v91
	v_mul_f32_e32 v88, v88, v103
	v_mul_f32_e32 v3, v89, v3
	v_mul_f32_e32 v88, v88, v90
	v_mul_f32_e32 v89, v3, v91
	s_nop 1
	v_fmac_f32_dpp v175, v175, v173 row_shr:1 row_mask:0xf bank_mask:0xf
	v_mul_f32_dpp v173, v173, v173 row_shr:1 row_mask:0xf bank_mask:0xf
	v_fmac_f32_dpp v177, v177, v174 row_shr:1 row_mask:0xf bank_mask:0xf
	v_mul_f32_dpp v174, v174, v174 row_shr:1 row_mask:0xf bank_mask:0xf
	s_nop 0
	global_load_dwordx4 v[38:41], v[38:39], off offset:448
	v_fmac_f32_dpp v184, v184, v181 row_shr:1 row_mask:0xf bank_mask:0xf
	v_mul_f32_dpp v181, v181, v181 row_shr:1 row_mask:0xf bank_mask:0xf
	v_fmac_f32_dpp v182, v182, v176 row_shr:1 row_mask:0xf bank_mask:0xf
	v_mul_f32_dpp v176, v176, v176 row_shr:1 row_mask:0xf bank_mask:0xf
	v_fmac_f32_dpp v175, v175, v173 row_shr:2 row_mask:0xf bank_mask:0xf
	v_mul_f32_dpp v173, v173, v173 row_shr:2 row_mask:0xf bank_mask:0xf
	v_fmac_f32_dpp v177, v177, v174 row_shr:2 row_mask:0xf bank_mask:0xf
	v_mul_f32_dpp v174, v174, v174 row_shr:2 row_mask:0xf bank_mask:0xf
	v_fmac_f32_dpp v184, v184, v181 row_shr:2 row_mask:0xf bank_mask:0xf
	v_mul_f32_dpp v181, v181, v181 row_shr:2 row_mask:0xf bank_mask:0xf
	v_fmac_f32_dpp v182, v182, v176 row_shr:2 row_mask:0xf bank_mask:0xf
	v_mul_f32_dpp v176, v176, v176 row_shr:2 row_mask:0xf bank_mask:0xf
	v_fmac_f32_dpp v175, v175, v173 row_shr:4 row_mask:0xf bank_mask:0xf
	v_mul_f32_dpp v173, v173, v173 row_shr:4 row_mask:0xf bank_mask:0xf
	v_fmac_f32_dpp v177, v177, v174 row_shr:4 row_mask:0xf bank_mask:0xf
	v_mad_u64_u32 v[162:163], s[24:25], v148, s13, v[126:127]
	v_mov_b32_e32 v148, v163
	v_mad_u64_u32 v[148:149], s[24:25], v149, s13, v[148:149]
	v_lshl_add_u64 v[150:151], v[124:125], 0, v[150:151]
	v_mov_b32_e32 v163, v148
	v_mul_f32_dpp v174, v174, v174 row_shr:4 row_mask:0xf bank_mask:0xf
	v_fmac_f32_dpp v184, v184, v181 row_shr:4 row_mask:0xf bank_mask:0xf
	v_mul_f32_dpp v181, v181, v181 row_shr:4 row_mask:0xf bank_mask:0xf
	v_fmac_f32_dpp v182, v182, v176 row_shr:4 row_mask:0xf bank_mask:0xf
	v_mul_f32_dpp v176, v176, v176 row_shr:4 row_mask:0xf bank_mask:0xf
	v_fmac_f32_dpp v175, v175, v173 row_shr:8 row_mask:0xf bank_mask:0xf
	v_mul_f32_dpp v173, v173, v173 row_shr:8 row_mask:0xf bank_mask:0xf
	v_fmac_f32_dpp v177, v177, v174 row_shr:8 row_mask:0xf bank_mask:0xf
	v_mul_f32_dpp v174, v174, v174 row_shr:8 row_mask:0xf bank_mask:0xf
	v_fmac_f32_dpp v184, v184, v181 row_shr:8 row_mask:0xf bank_mask:0xf
	v_mul_f32_dpp v181, v181, v181 row_shr:8 row_mask:0xf bank_mask:0xf
	v_fmac_f32_dpp v182, v182, v176 row_shr:8 row_mask:0xf bank_mask:0xf
	v_mul_f32_dpp v176, v176, v176 row_shr:8 row_mask:0xf bank_mask:0xf

; __device__ __forceinline__ void lru_fused(const bf16* XC, const bf16* Wrg_t, const bf16* PROJ, bf16* YL, const float* b_a, const float* b_x, const float* sp8,
;                                           LAS unsigned char* lds, int tid, int lane, int wave, int vcu, int G) {
;     ...
; #pragma unroll
;             for (int r2 = 0; r2 < 2; ++r2)
; #pragma unroll
;                 for (int c2 = 0; c2 < 2; ++c2)
;                     asm volatile("s_nop 1\n\t" LRU_STEP(1) LRU_STEP(2) LRU_STEP(4) LRU_STEP(8)
;                                  : "+v"(A[r2][c2][0]), "+v"(A[r2][c2][1]), "+v"(A[r2][c2][2]), "+v"(A[r2][c2][3]), "+v"(U[r2][c2][0]), "+v"(U[r2][c2][1]), "+v"(U[r2][c2][2]), "+v"(U[r2][c2][3]));
;     ...
;             const int l15 = (lane & 48) | 15;
; #pragma unroll
;             for (int c2 = 0; c2 < 2; ++c2)
; #pragma unroll
;                 for (int j = 0; j < 4; ++j) { const float a15 = __shfl(A[0][c2][j], l15), u15 = __shfl(U[0][c2][j], l15);
	ds_bpermute_b32 v90, v172, v173
	ds_bpermute_b32 v102, v172, v175
	s_nop 0
	global_load_dwordx4 v[160:163], v[162:163], off
	ds_bpermute_b32 v103, v172, v177
	ds_bpermute_b32 v91, v172, v174
	ds_bpermute_b32 v104, v172, v184
	ds_bpermute_b32 v105, v172, v182
	s_nop 1
	v_fmac_f32_dpp v186, v186, v183 row_shr:1 row_mask:0xf bank_mask:0xf
	v_mul_f32_dpp v183, v183, v183 row_shr:1 row_mask:0xf bank_mask:0xf
	v_fmac_f32_dpp v188, v188, v185 row_shr:1 row_mask:0xf bank_mask:0xf
	v_mul_f32_dpp v185, v185, v185 row_shr:1 row_mask:0xf bank_mask:0xf
	v_fmac_f32_dpp v191, v191, v189 row_shr:1 row_mask:0xf bank_mask:0xf
	v_mul_f32_dpp v189, v189, v189 row_shr:1 row_mask:0xf bank_mask:0xf
	v_fmac_f32_dpp v190, v190, v187 row_shr:1 row_mask:0xf bank_mask:0xf
	v_mul_f32_dpp v187, v187, v187 row_shr:1 row_mask:0xf bank_mask:0xf
	v_fmac_f32_dpp v186, v186, v183 row_shr:2 row_mask:0xf bank_mask:0xf
	v_mul_f32_dpp v183, v183, v183 row_shr:2 row_mask:0xf bank_mask:0xf
	v_fmac_f32_dpp v188, v188, v185 row_shr:2 row_mask:0xf bank_mask:0xf
	v_mul_f32_dpp v185, v185, v185 row_shr:2 row_mask:0xf bank_mask:0xf
	v_fmac_f32_dpp v191, v191, v189 row_shr:2 row_mask:0xf bank_mask:0xf
	v_mul_f32_dpp v189, v189, v189 row_shr:2 row_mask:0xf bank_mask:0xf
	v_fmac_f32_dpp v190, v190, v187 row_shr:2 row_mask:0xf bank_mask:0xf
	v_mul_f32_dpp v187, v187, v187 row_shr:2 row_mask:0xf bank_mask:0xf
	v_fmac_f32_dpp v186, v186, v183 row_shr:4 row_mask:0xf bank_mask:0xf
	v_mul_f32_dpp v183, v183, v183 row_shr:4 row_mask:0xf bank_mask:0xf
	v_fmac_f32_dpp v188, v188, v185 row_shr:4 row_mask:0xf bank_mask:0xf
	v_mul_f32_dpp v185, v185, v185 row_shr:4 row_mask:0xf bank_mask:0xf
	v_fmac_f32_dpp v191, v191, v189 row_shr:4 row_mask:0xf bank_mask:0xf
	v_mul_f32_dpp v189, v189, v189 row_shr:4 row_mask:0xf bank_mask:0xf
	v_fmac_f32_dpp v190, v190, v187 row_shr:4 row_mask:0xf bank_mask:0xf
	v_mul_f32_dpp v187, v187, v187 row_shr:4 row_mask:0xf bank_mask:0xf
	v_fmac_f32_dpp v186, v186, v183 row_shr:8 row_mask:0xf bank_mask:0xf
	v_mul_f32_dpp v183, v183, v183 row_shr:8 row_mask:0xf bank_mask:0xf
	v_fmac_f32_dpp v188, v188, v185 row_shr:8 row_mask:0xf bank_mask:0xf
	v_mul_f32_dpp v185, v185, v185 row_shr:8 row_mask:0xf bank_mask:0xf
	v_fmac_f32_dpp v191, v191, v189 row_shr:8 row_mask:0xf bank_mask:0xf
	v_mul_f32_dpp v189, v189, v189 row_shr:8 row_mask:0xf bank_mask:0xf
	v_fmac_f32_dpp v190, v190, v187 row_shr:8 row_mask:0xf bank_mask:0xf
	v_mul_f32_dpp v187, v187, v187 row_shr:8 row_mask:0xf bank_mask:0xf

; __device__ __forceinline__ void lru_fused(const bf16* XC, const bf16* Wrg_t, const bf16* PROJ, bf16* YL, const float* b_a, const float* b_x, const float* sp8,
;                                           LAS unsigned char* lds, int tid, int lane, int wave, int vcu, int G) {
;     ...
; #pragma unroll
;             for (int r2 = 0; r2 < 2; ++r2)
; #pragma unroll
;                 for (int c2 = 0; c2 < 2; ++c2)
;                     asm volatile("s_nop 1\n\t" LRU_STEP(1) LRU_STEP(2) LRU_STEP(4) LRU_STEP(8)
;                                  : "+v"(A[r2][c2][0]), "+v"(A[r2][c2][1]), "+v"(A[r2][c2][2]), "+v"(A[r2][c2][3]), "+v"(U[r2][c2][0]), "+v"(U[r2][c2][1]), "+v"(U[r2][c2][2]), "+v"(U[r2][c2][3]));
	s_nop 1
	v_fmac_f32_dpp v94, v94, v98 row_shr:1 row_mask:0xf bank_mask:0xf
	v_mul_f32_dpp v98, v98, v98 row_shr:1 row_mask:0xf bank_mask:0xf
	v_fmac_f32_dpp v95, v95, v99 row_shr:1 row_mask:0xf bank_mask:0xf
	v_mul_f32_dpp v99, v99, v99 row_shr:1 row_mask:0xf bank_mask:0xf
	v_fmac_f32_dpp v96, v96, v100 row_shr:1 row_mask:0xf bank_mask:0xf
	v_mul_f32_dpp v100, v100, v100 row_shr:1 row_mask:0xf bank_mask:0xf
	v_fmac_f32_dpp v97, v97, v101 row_shr:1 row_mask:0xf bank_mask:0xf
	v_mul_f32_dpp v101, v101, v101 row_shr:1 row_mask:0xf bank_mask:0xf
	v_fmac_f32_dpp v94, v94, v98 row_shr:2 row_mask:0xf bank_mask:0xf
	v_mul_f32_dpp v98, v98, v98 row_shr:2 row_mask:0xf bank_mask:0xf
	v_fmac_f32_dpp v95, v95, v99 row_shr:2 row_mask:0xf bank_mask:0xf
	v_mul_f32_dpp v99, v99, v99 row_shr:2 row_mask:0xf bank_mask:0xf
	v_fmac_f32_dpp v96, v96, v100 row_shr:2 row_mask:0xf bank_mask:0xf
	v_mul_f32_dpp v100, v100, v100 row_shr:2 row_mask:0xf bank_mask:0xf
	v_fmac_f32_dpp v97, v97, v101 row_shr:2 row_mask:0xf bank_mask:0xf
	v_mul_f32_dpp v101, v101, v101 row_shr:2 row_mask:0xf bank_mask:0xf
	v_fmac_f32_dpp v94, v94, v98 row_shr:4 row_mask:0xf bank_mask:0xf
	v_mul_f32_dpp v98, v98, v98 row_shr:4 row_mask:0xf bank_mask:0xf
	v_fmac_f32_dpp v95, v95, v99 row_shr:4 row_mask:0xf bank_mask:0xf
	v_mul_f32_dpp v99, v99, v99 row_shr:4 row_mask:0xf bank_mask:0xf
	v_fmac_f32_dpp v96, v96, v100 row_shr:4 row_mask:0xf bank_mask:0xf
	v_mul_f32_dpp v100, v100, v100 row_shr:4 row_mask:0xf bank_mask:0xf
	v_fmac_f32_dpp v97, v97, v101 row_shr:4 row_mask:0xf bank_mask:0xf
	v_mul_f32_dpp v101, v101, v101 row_shr:4 row_mask:0xf bank_mask:0xf
	v_fmac_f32_dpp v94, v94, v98 row_shr:8 row_mask:0xf bank_mask:0xf
	v_mul_f32_dpp v98, v98, v98 row_shr:8 row_mask:0xf bank_mask:0xf
	v_fmac_f32_dpp v95, v95, v99 row_shr:8 row_mask:0xf bank_mask:0xf
	v_mul_f32_dpp v99, v99, v99 row_shr:8 row_mask:0xf bank_mask:0xf
	v_fmac_f32_dpp v96, v96, v100 row_shr:8 row_mask:0xf bank_mask:0xf
	v_mul_f32_dpp v100, v100, v100 row_shr:8 row_mask:0xf bank_mask:0xf
	v_fmac_f32_dpp v97, v97, v101 row_shr:8 row_mask:0xf bank_mask:0xf
	v_mul_f32_dpp v101, v101, v101 row_shr:8 row_mask:0xf bank_mask:0xf

; __device__ __forceinline__ void lru_fused(const bf16* XC, const bf16* Wrg_t, const bf16* PROJ, bf16* YL, const float* b_a, const float* b_x, const float* sp8,
;                                           LAS unsigned char* lds, int tid, int lane, int wave, int vcu, int G) {
;     ...
;             for (int r2 = 0; r2 < 2; ++r2)
; #pragma unroll
;                 for (int c2 = 0; c2 < 2; ++c2)
;                     asm volatile("s_nop 1\n\t" LRU_STEP(1) LRU_STEP(2) LRU_STEP(4) LRU_STEP(8)
;                                  : "+v"(A[r2][c2][0]), "+v"(A[r2][c2][1]), "+v"(A[r2][c2][2]), "+v"(A[r2][c2][3]), "+v"(U[r2][c2][0]), "+v"(U[r2][c2][1]), "+v"(U[r2][c2][2]), "+v"(U[r2][c2][3]));
;     ...
;             const int l15 = (lane & 48) | 15;
; #pragma unroll
;             for (int c2 = 0; c2 < 2; ++c2)
; #pragma unroll
;                 for (int j = 0; j < 4; ++j) { const float a15 = __shfl(A[0][c2][j], l15), u15 = __shfl(U[0][c2][j], l15);
;                     U[1][c2][j] = A[1][c2][j] * u15 + U[1][c2][j]; A[1][c2][j] = A[1][c2][j] * a15; }
	ds_bpermute_b32 v106, v172, v189
	s_waitcnt lgkmcnt(4)
	v_pk_fma_f32 v[94:95], v[98:99], v[102:103], v[94:95]
	s_waitcnt lgkmcnt(3)
	v_pk_mul_f32 v[98:99], v[98:99], v[90:91]
	ds_bpermute_b32 v90, v172, v181
	ds_bpermute_b32 v91, v172, v176
	s_waitcnt lgkmcnt(3)
	v_pk_fma_f32 v[96:97], v[100:101], v[104:105], v[96:97]
	ds_bpermute_b32 v102, v172, v183
	ds_bpermute_b32 v104, v172, v186
	ds_bpermute_b32 v103, v172, v185
	ds_bpermute_b32 v105, v172, v188
	ds_bpermute_b32 v108, v172, v191
	ds_bpermute_b32 v109, v172, v190
	ds_bpermute_b32 v107, v172, v187
	s_and_b32 s24, s22, 1
	s_nop 1
	v_fmac_f32_dpp v86, v86, v4 row_shr:1 row_mask:0xf bank_mask:0xf
	v_mul_f32_dpp v4, v4, v4 row_shr:1 row_mask:0xf bank_mask:0xf
	v_fmac_f32_dpp v87, v87, v5 row_shr:1 row_mask:0xf bank_mask:0xf
	v_mul_f32_dpp v5, v5, v5 row_shr:1 row_mask:0xf bank_mask:0xf
	v_fmac_f32_dpp v88, v88, v92 row_shr:1 row_mask:0xf bank_mask:0xf
	v_mul_f32_dpp v92, v92, v92 row_shr:1 row_mask:0xf bank_mask:0xf
	v_fmac_f32_dpp v89, v89, v93 row_shr:1 row_mask:0xf bank_mask:0xf
	v_mul_f32_dpp v93, v93, v93 row_shr:1 row_mask:0xf bank_mask:0xf
	v_fmac_f32_dpp v86, v86, v4 row_shr:2 row_mask:0xf bank_mask:0xf
	v_mul_f32_dpp v4, v4, v4 row_shr:2 row_mask:0xf bank_mask:0xf
	v_fmac_f32_dpp v87, v87, v5 row_shr:2 row_mask:0xf bank_mask:0xf
	v_mul_f32_dpp v5, v5, v5 row_shr:2 row_mask:0xf bank_mask:0xf
	v_fmac_f32_dpp v88, v88, v92 row_shr:2 row_mask:0xf bank_mask:0xf
	v_mul_f32_dpp v92, v92, v92 row_shr:2 row_mask:0xf bank_mask:0xf
	v_fmac_f32_dpp v89, v89, v93 row_shr:2 row_mask:0xf bank_mask:0xf
	v_mul_f32_dpp v93, v93, v93 row_shr:2 row_mask:0xf bank_mask:0xf
	v_fmac_f32_dpp v86, v86, v4 row_shr:4 row_mask:0xf bank_mask:0xf
	v_mul_f32_dpp v4, v4, v4 row_shr:4 row_mask:0xf bank_mask:0xf
	v_fmac_f32_dpp v87, v87, v5 row_shr:4 row_mask:0xf bank_mask:0xf
	v_mul_f32_dpp v5, v5, v5 row_shr:4 row_mask:0xf bank_mask:0xf
	v_fmac_f32_dpp v88, v88, v92 row_shr:4 row_mask:0xf bank_mask:0xf
	v_mul_f32_dpp v92, v92, v92 row_shr:4 row_mask:0xf bank_mask:0xf
	v_fmac_f32_dpp v89, v89, v93 row_shr:4 row_mask:0xf bank_mask:0xf
	v_mul_f32_dpp v93, v93, v93 row_shr:4 row_mask:0xf bank_mask:0xf
	v_fmac_f32_dpp v86, v86, v4 row_shr:8 row_mask:0xf bank_mask:0xf
	v_mul_f32_dpp v4, v4, v4 row_shr:8 row_mask:0xf bank_mask:0xf
	v_fmac_f32_dpp v87, v87, v5 row_shr:8 row_mask:0xf bank_mask:0xf
	v_mul_f32_dpp v5, v5, v5 row_shr:8 row_mask:0xf bank_mask:0xf
	v_fmac_f32_dpp v88, v88, v92 row_shr:8 row_mask:0xf bank_mask:0xf
	v_mul_f32_dpp v92, v92, v92 row_shr:8 row_mask:0xf bank_mask:0xf
	v_fmac_f32_dpp v89, v89, v93 row_shr:8 row_mask:0xf bank_mask:0xf
	v_mul_f32_dpp v93, v93, v93 row_shr:8 row_mask:0xf bank_mask:0xf

; #define LAS __attribute__((address_space(3)))
; __device__ __forceinline__ void lru_fused(const bf16* XC, const bf16* Wrg_t, const bf16* PROJ, bf16* YL, const float* b_a, const float* b_x, const float* sp8,
;                                           LAS unsigned char* lds, int tid, int lane, int wave, int vcu, int G) {
;     ...
;             const int l15 = (lane & 48) | 15;
; #pragma unroll
;             for (int c2 = 0; c2 < 2; ++c2)
; #pragma unroll
;                 for (int j = 0; j < 4; ++j) { const float a15 = __shfl(A[0][c2][j], l15), u15 = __shfl(U[0][c2][j], l15);
;                     U[1][c2][j] = A[1][c2][j] * u15 + U[1][c2][j]; A[1][c2][j] = A[1][c2][j] * a15; }
;             LAS float* xp = xch + (i & 1) * 512;
;             if (fr == 15) {
; #pragma unroll
;                 for (int c2 = 0; c2 < 2; ++c2) { *(LAS f32x4*)(xp + wave * 32 + 16 * c2 + 4 * fq) = (f32x4){A[1][c2][0], A[1][c2][1], A[1][c2][2], A[1][c2][3]};
;                     *(LAS f32x4*)(xp + 256 + wave * 32 + 16 * c2 + 4 * fq) = (f32x4){U[1][c2][0], U[1][c2][1], U[1][c2][2], U[1][c2][3]}; } }
	s_lshl_b32 s23, s24, 11
	s_waitcnt lgkmcnt(7)
	v_pk_mul_f32 v[100:101], v[100:101], v[90:91]
	s_waitcnt lgkmcnt(3)
	v_pk_fma_f32 v[86:87], v[4:5], v[104:105], v[86:87]
	v_pk_mul_f32 v[90:91], v[4:5], v[102:103]
	s_waitcnt lgkmcnt(1)
	v_pk_fma_f32 v[88:89], v[92:93], v[108:109], v[88:89]
	s_waitcnt lgkmcnt(0)
	v_pk_mul_f32 v[92:93], v[92:93], v[106:107]
	s_add_i32 s23, s23, 0
	s_and_saveexec_b64 s[66:67], s[2:3]
	s_cbranch_execz .LBB0_458
	s_lshl_b32 s25, s6, 2
	s_add_i32 s25, s23, s25
	v_lshl_add_u32 v3, v165, 2, s25
	ds_write_b128 v3, v[98:101] offset:36864
	ds_write_b128 v3, v[94:97] offset:37888
	ds_write_b128 v3, v[90:93] offset:36928
	ds_write_b128 v3, v[86:89] offset:37952

; __global__ void __launch_bounds__(NWAVES * 64, 2) fwd_kernel(Args args) {
	.amdhsa_kernel _Z10fwd_kernel4Args
		.amdhsa_group_segment_fixed_size 0
		.amdhsa_private_segment_fixed_size 0
		.amdhsa_kernarg_size 472
		.amdhsa_user_sgpr_count 2
		.amdhsa_user_sgpr_dispatch_ptr 0
		.amdhsa_user_sgpr_queue_ptr 0
		.amdhsa_user_sgpr_kernarg_segment_ptr 1
		.amdhsa_user_sgpr_dispatch_id 0
		.amdhsa_user_sgpr_kernarg_preload_length 0
		.amdhsa_user_sgpr_kernarg_preload_offset 0
		.amdhsa_user_sgpr_private_segment_size 0
		.amdhsa_uses_dynamic_stack 0
		.amdhsa_enable_private_segment 0
		.amdhsa_system_sgpr_workgroup_id_x 1
		.amdhsa_system_sgpr_workgroup_id_y 0
		.amdhsa_system_sgpr_workgroup_id_z 0
		.amdhsa_system_sgpr_workgroup_info 0
		.amdhsa_system_vgpr_workitem_id 0
		.amdhsa_next_free_vgpr 256
		.amdhsa_next_free_sgpr 98
		.amdhsa_accum_offset 256
		.amdhsa_reserve_vcc 1
		.amdhsa_float_round_mode_32 0
		.amdhsa_float_round_mode_16_64 0
		.amdhsa_float_denorm_mode_32 3
		.amdhsa_float_denorm_mode_16_64 3
		.amdhsa_dx10_clamp 1
		.amdhsa_ieee_mode 1
		.amdhsa_fp16_overflow 0
		.amdhsa_tg_split 0
		.amdhsa_exception_fp_ieee_invalid_op 0
		.amdhsa_exception_fp_denorm_src 0
		.amdhsa_exception_fp_ieee_div_zero 0
		.amdhsa_exception_fp_ieee_overflow 0
		.amdhsa_exception_fp_ieee_underflow 0
		.amdhsa_exception_fp_ieee_inexact 0
		.amdhsa_exception_int_div_zero 0
	.end_amdhsa_kernel

; __global__ void __launch_bounds__(NWAVES * 64, 2) fwd_kernel(Args args) {
amdhsa.kernels:
  - .agpr_count:     0
    .args:
      - .offset:         0
        .size:           216
        .value_kind:     by_value
      - .offset:         216
        .size:           4
        .value_kind:     hidden_block_count_x
      - .offset:         220
        .size:           4
        .value_kind:     hidden_block_count_y
      - .offset:         224
        .size:           4
        .value_kind:     hidden_block_count_z
      - .offset:         228
        .size:           2
        .value_kind:     hidden_group_size_x
      - .offset:         230
        .size:           2
        .value_kind:     hidden_group_size_y
      - .offset:         232
        .size:           2
        .value_kind:     hidden_group_size_z
      - .offset:         234
        .size:           2
        .value_kind:     hidden_remainder_x
      - .offset:         236
        .size:           2
        .value_kind:     hidden_remainder_y
      - .offset:         238
        .size:           2
        .value_kind:     hidden_remainder_z
      - .offset:         256
        .size:           8
        .value_kind:     hidden_global_offset_x
      - .offset:         264
        .size:           8
        .value_kind:     hidden_global_offset_y
      - .offset:         272
        .size:           8
        .value_kind:     hidden_global_offset_z
      - .offset:         280
        .size:           2
        .value_kind:     hidden_grid_dims
      - .offset:         336
        .size:           4
        .value_kind:     hidden_dynamic_lds_size
    .group_segment_fixed_size: 0
    .kernarg_segment_align: 8
    .kernarg_segment_size: 472
    .language:       OpenCL C
    .language_version:
      - 2
      - 0
    .max_flat_workgroup_size: 512
    .name:           _Z10fwd_kernel4Args
    .private_segment_fixed_size: 0
    .sgpr_count:     104
    .sgpr_spill_count: 81
    .symbol:         _Z10fwd_kernel4Args.kd
    .uniform_work_group_size: 1
    .uses_dynamic_stack: false
    .vgpr_count:     256
    .vgpr_spill_count: 0
    .wavefront_size: 64
